# v26: v25 with the three staging stores spread one per QK MFMA gap (behind MFMAs 4, 5 and 6)
# speedup vs baseline: 1.0087x; 1.0035x over previous
.LBB0_36:
	s_add_i32 s23, s10, -1
	s_and_b32 s23, s23, 1
	s_sub_i32 s26, s22, 63
	s_cmp_gt_u32 s26, s5
	s_cbranch_scc1 .LBB0_43
	s_mul_i32 s26, s23, 0x7400
	s_add_i32 s26, s26, 0
	s_xor_b32 s78, s23, 1
	s_mulk_i32 s78, 0x7400
	s_cmp_le_u32 s22, s1
	v_add3_u32 v190, s26, v165, v172
	ds_read_b128 v[98:101], v190
	ds_read_b128 v[102:105], v190 offset:32
	ds_read_b128 v[106:109], v190 offset:64
	ds_read_b128 v[110:113], v190 offset:96
	ds_read_b128 v[240:243], v190 offset:4608
	ds_read_b128 v[244:247], v190 offset:4640
	ds_read_b128 v[214:217], v190 offset:4672
	ds_read_b128 v[190:193], v190 offset:4704
	s_setprio 1
	s_waitcnt lgkmcnt(7)
	v_mfma_f32_32x32x16_bf16 v[82:97], v[98:101], v[126:129], v[66:81]
	s_waitcnt lgkmcnt(6)
	v_mfma_f32_32x32x16_bf16 v[82:97], v[102:105], v[130:133], v[82:97]
	s_waitcnt lgkmcnt(5)
	v_mfma_f32_32x32x16_bf16 v[82:97], v[106:109], v[134:137], v[82:97]
	s_waitcnt lgkmcnt(4)
	v_mfma_f32_32x32x16_bf16 v[82:97], v[110:113], v[138:141], v[82:97]
	v_add3_u32 v166, s78, v163, v0
	v_add_u32_e32 v167, s78, v144
	v_add_u32_e32 v168, v167, v164
	v_add_u32_e32 v167, v167, v175
	s_waitcnt vmcnt(2)
	ds_write_b128 v166, v[114:117]
	s_waitcnt lgkmcnt(4)
	v_mfma_f32_32x32x16_bf16 v[98:113], v[240:243], v[126:129], v[66:81]
	s_waitcnt vmcnt(1)
	ds_write_b128 v168, v[118:121] offset:9216
	s_waitcnt lgkmcnt(4)
	v_mfma_f32_32x32x16_bf16 v[98:113], v[244:247], v[130:133], v[98:113]
	s_waitcnt vmcnt(0)
	ds_write_b128 v167, v[122:125] offset:9216
	s_waitcnt lgkmcnt(4)
	v_mfma_f32_32x32x16_bf16 v[98:113], v[214:217], v[134:137], v[98:113]
	s_waitcnt lgkmcnt(3)
	v_mfma_f32_32x32x16_bf16 v[98:113], v[190:193], v[138:141], v[98:113]
	s_setprio 0
	s_cbranch_scc1 .LBB0_39
	v_add_u32_e32 v190, s22, v173
	v_subrev_u32_e32 v191, 63, v190
	v_cmp_le_i32_e32 vcc, v191, v179
	v_subrev_u32_e32 v192, 61, v190
	v_subrev_u32_e32 v190, 60, v190
	s_nop 5
	v_cndmask_b32_e32 v98, v220, v98, vcc
	v_cmp_lt_i32_e32 vcc, v191, v176
	s_nop 1
	v_cndmask_b32_e32 v83, v220, v83, vcc
	v_cmp_le_i32_e32 vcc, v191, v176
	s_nop 1
	v_cndmask_b32_e32 v82, v220, v82, vcc
	v_cmp_le_i32_e32 vcc, v191, v180
	s_nop 1
	v_cndmask_b32_e32 v99, v220, v99, vcc
	v_cmp_le_i32_e32 vcc, v192, v176
	s_nop 1
	v_cndmask_b32_e32 v84, v220, v84, vcc
	v_cmp_le_i32_e32 vcc, v191, v181
	s_nop 1
	v_cndmask_b32_e32 v100, v220, v100, vcc
	v_cmp_le_i32_e32 vcc, v190, v176
	s_nop 1
	v_cndmask_b32_e32 v85, v220, v85, vcc
	v_cmp_le_i32_e32 vcc, v191, v182
	s_nop 1
	v_cndmask_b32_e32 v101, v220, v101, vcc
	v_cmp_le_i32_e32 vcc, v191, v183
	s_nop 1
	v_cndmask_b32_e32 v86, v220, v86, vcc
	v_cmp_le_i32_e32 vcc, v191, v184
	s_nop 1
	v_cndmask_b32_e32 v102, v220, v102, vcc
	v_cmp_le_i32_e32 vcc, v191, v185
	s_nop 1
	v_cndmask_b32_e32 v87, v220, v87, vcc
	v_cmp_le_i32_e32 vcc, v191, v186
	s_nop 1
	v_cndmask_b32_e32 v103, v220, v103, vcc
	v_cmp_le_i32_e32 vcc, v191, v187
	s_nop 1
	v_cndmask_b32_e32 v88, v220, v88, vcc
	v_cmp_le_i32_e32 vcc, v191, v188
	s_nop 1
	v_cndmask_b32_e32 v104, v220, v104, vcc
	v_cmp_le_i32_e32 vcc, v191, v189
	s_nop 1
	v_cndmask_b32_e32 v89, v220, v89, vcc
	v_cmp_le_i32_e32 vcc, v191, v195
	s_nop 1
	v_cndmask_b32_e32 v105, v220, v105, vcc
	v_cmp_le_i32_e32 vcc, v191, v196
	s_nop 1
	v_cndmask_b32_e32 v90, v220, v90, vcc
	v_cmp_le_i32_e32 vcc, v191, v197
	s_nop 1
	v_cndmask_b32_e32 v106, v220, v106, vcc
	v_cmp_le_i32_e32 vcc, v191, v198
	s_nop 1
	v_cndmask_b32_e32 v91, v220, v91, vcc
	v_cmp_le_i32_e32 vcc, v191, v199
	s_nop 1
	v_cndmask_b32_e32 v107, v220, v107, vcc
	v_cmp_le_i32_e32 vcc, v191, v200
	s_nop 1
	v_cndmask_b32_e32 v92, v220, v92, vcc
	v_cmp_le_i32_e32 vcc, v191, v201
	s_nop 1
	v_cndmask_b32_e32 v108, v220, v108, vcc
	v_cmp_le_i32_e32 vcc, v191, v202
	s_nop 1
	v_cndmask_b32_e32 v93, v220, v93, vcc
	v_cmp_le_i32_e32 vcc, v191, v203
	s_nop 1
	v_cndmask_b32_e32 v109, v220, v109, vcc
	v_cmp_le_i32_e32 vcc, v191, v204
	s_nop 1
	v_cndmask_b32_e32 v94, v220, v94, vcc
	v_cmp_le_i32_e32 vcc, v191, v205
	s_nop 1
	v_cndmask_b32_e32 v110, v220, v110, vcc
	v_cmp_le_i32_e32 vcc, v191, v228
	s_nop 1
	v_cndmask_b32_e32 v95, v220, v95, vcc
	v_cmp_le_i32_e32 vcc, v191, v229
	s_nop 1
	v_cndmask_b32_e32 v111, v220, v111, vcc
	v_cmp_le_i32_e32 vcc, v191, v230
	s_nop 1
	v_cndmask_b32_e32 v96, v220, v96, vcc
	v_cmp_le_i32_e32 vcc, v191, v231
	s_nop 1
	v_cndmask_b32_e32 v112, v220, v112, vcc
	v_cmp_le_i32_e32 vcc, v191, v232
	s_nop 1
	v_cndmask_b32_e32 v97, v220, v97, vcc
	v_cmp_le_i32_e32 vcc, v191, v233
	s_nop 1
	v_cndmask_b32_e32 v113, v220, v113, vcc

.LBB0_51:
	s_add_i32 s23, s22, -1
	s_and_b32 s23, s23, 1
	s_sub_i32 s26, s10, 63
	s_cmp_gt_u32 s26, s5
	s_cbranch_scc1 .LBB0_58
	s_mul_i32 s26, s23, 0x7400
	s_add_i32 s26, s26, 0
	s_xor_b32 s78, s23, 1
	s_mulk_i32 s78, 0x7400
	s_cmp_le_u32 s10, s1
	v_add3_u32 v152, s26, v165, v172
	ds_read_b128 v[98:101], v152
	ds_read_b128 v[102:105], v152 offset:32
	ds_read_b128 v[106:109], v152 offset:64
	ds_read_b128 v[110:113], v152 offset:96
	ds_read_b128 v[154:157], v152 offset:4608
	ds_read_b128 v[190:193], v152 offset:4640
	ds_read_b128 v[214:217], v152 offset:4672
	ds_read_b128 v[234:237], v152 offset:4704
	s_setprio 1
	s_waitcnt lgkmcnt(7)
	v_mfma_f32_32x32x16_bf16 v[82:97], v[98:101], v[114:117], v[66:81]
	s_waitcnt lgkmcnt(6)
	v_mfma_f32_32x32x16_bf16 v[82:97], v[102:105], v[118:121], v[82:97]
	s_waitcnt lgkmcnt(5)
	v_mfma_f32_32x32x16_bf16 v[82:97], v[106:109], v[126:129], v[82:97]
	s_waitcnt lgkmcnt(4)
	v_mfma_f32_32x32x16_bf16 v[82:97], v[110:113], v[130:133], v[82:97]
	v_add3_u32 v166, s78, v163, v0
	v_add_u32_e32 v167, s78, v144
	v_add_u32_e32 v168, v167, v164
	v_add_u32_e32 v167, v167, v175
	s_waitcnt vmcnt(2)
	ds_write_b128 v166, v[122:125]
	s_waitcnt lgkmcnt(4)
	v_mfma_f32_32x32x16_bf16 v[98:113], v[154:157], v[114:117], v[66:81]
	s_waitcnt vmcnt(1)
	ds_write_b128 v168, v[134:137] offset:9216
	s_waitcnt lgkmcnt(4)
	v_mfma_f32_32x32x16_bf16 v[98:113], v[190:193], v[118:121], v[98:113]
	s_waitcnt vmcnt(0)
	ds_write_b128 v167, v[138:141] offset:9216
	s_waitcnt lgkmcnt(4)
	v_mfma_f32_32x32x16_bf16 v[98:113], v[214:217], v[126:129], v[98:113]
	s_waitcnt lgkmcnt(3)
	v_mfma_f32_32x32x16_bf16 v[98:113], v[234:237], v[130:133], v[98:113]
	s_setprio 0
	s_cbranch_scc1 .LBB0_54
	v_add_u32_e32 v152, s10, v173
	v_subrev_u32_e32 v154, 63, v152
	v_cmp_le_i32_e32 vcc, v154, v179
	v_subrev_u32_e32 v155, 61, v152
	v_subrev_u32_e32 v152, 60, v152
	s_nop 5
	v_cndmask_b32_e32 v98, v220, v98, vcc
	v_cmp_lt_i32_e32 vcc, v154, v176
	s_nop 1
	v_cndmask_b32_e32 v83, v220, v83, vcc
	v_cmp_le_i32_e32 vcc, v154, v176
	s_nop 1
	v_cndmask_b32_e32 v82, v220, v82, vcc
	v_cmp_le_i32_e32 vcc, v154, v180
	s_nop 1
	v_cndmask_b32_e32 v99, v220, v99, vcc
	v_cmp_le_i32_e32 vcc, v155, v176
	s_nop 1
	v_cndmask_b32_e32 v84, v220, v84, vcc
	v_cmp_le_i32_e32 vcc, v154, v181
	s_nop 1
	v_cndmask_b32_e32 v100, v220, v100, vcc
	v_cmp_le_i32_e32 vcc, v152, v176
	s_nop 1
	v_cndmask_b32_e32 v85, v220, v85, vcc
	v_cmp_le_i32_e32 vcc, v154, v182
	s_nop 1
	v_cndmask_b32_e32 v101, v220, v101, vcc
	v_cmp_le_i32_e32 vcc, v154, v183
	s_nop 1
	v_cndmask_b32_e32 v86, v220, v86, vcc
	v_cmp_le_i32_e32 vcc, v154, v184
	s_nop 1
	v_cndmask_b32_e32 v102, v220, v102, vcc
	v_cmp_le_i32_e32 vcc, v154, v185
	s_nop 1
	v_cndmask_b32_e32 v87, v220, v87, vcc
	v_cmp_le_i32_e32 vcc, v154, v186
	s_nop 1
	v_cndmask_b32_e32 v103, v220, v103, vcc
	v_cmp_le_i32_e32 vcc, v154, v187
	s_nop 1
	v_cndmask_b32_e32 v88, v220, v88, vcc
	v_cmp_le_i32_e32 vcc, v154, v188
	s_nop 1
	v_cndmask_b32_e32 v104, v220, v104, vcc
	v_cmp_le_i32_e32 vcc, v154, v189
	s_nop 1
	v_cndmask_b32_e32 v89, v220, v89, vcc
	v_cmp_le_i32_e32 vcc, v154, v195
	s_nop 1
	v_cndmask_b32_e32 v105, v220, v105, vcc
	v_cmp_le_i32_e32 vcc, v154, v196
	s_nop 1
	v_cndmask_b32_e32 v90, v220, v90, vcc
	v_cmp_le_i32_e32 vcc, v154, v197
	s_nop 1
	v_cndmask_b32_e32 v106, v220, v106, vcc
	v_cmp_le_i32_e32 vcc, v154, v198
	s_nop 1
	v_cndmask_b32_e32 v91, v220, v91, vcc
	v_cmp_le_i32_e32 vcc, v154, v199
	s_nop 1
	v_cndmask_b32_e32 v107, v220, v107, vcc
	v_cmp_le_i32_e32 vcc, v154, v200
	s_nop 1
	v_cndmask_b32_e32 v92, v220, v92, vcc
	v_cmp_le_i32_e32 vcc, v154, v201
	s_nop 1
	v_cndmask_b32_e32 v108, v220, v108, vcc
	v_cmp_le_i32_e32 vcc, v154, v202
	s_nop 1
	v_cndmask_b32_e32 v93, v220, v93, vcc
	v_cmp_le_i32_e32 vcc, v154, v203
	s_nop 1
	v_cndmask_b32_e32 v109, v220, v109, vcc
	v_cmp_le_i32_e32 vcc, v154, v204
	s_nop 1
	v_cndmask_b32_e32 v94, v220, v94, vcc
	v_cmp_le_i32_e32 vcc, v154, v205
	s_nop 1
	v_cndmask_b32_e32 v110, v220, v110, vcc
	v_cmp_le_i32_e32 vcc, v154, v228
	s_nop 1
	v_cndmask_b32_e32 v95, v220, v95, vcc
	v_cmp_le_i32_e32 vcc, v154, v229
	s_nop 1
	v_cndmask_b32_e32 v111, v220, v111, vcc
	v_cmp_le_i32_e32 vcc, v154, v230
	s_nop 1
	v_cndmask_b32_e32 v96, v220, v96, vcc
	v_cmp_le_i32_e32 vcc, v154, v231
	s_nop 1
	v_cndmask_b32_e32 v112, v220, v112, vcc
	v_cmp_le_i32_e32 vcc, v154, v232
	s_nop 1
	v_cndmask_b32_e32 v97, v220, v97, vcc
	v_cmp_le_i32_e32 vcc, v154, v233
	s_nop 1
	v_cndmask_b32_e32 v113, v220, v113, vcc

.LBB0_66:
	s_add_i32 s23, s4, -1
	s_and_b32 s23, s23, 1
	s_cmp_gt_u32 s22, s11
	s_cbranch_scc1 .LBB0_73
	s_mul_i32 s26, s23, 0x7400
	s_add_i32 s26, s26, 0
	s_add_i32 s30, s22, 63
	s_xor_b32 s78, s23, 1
	s_mulk_i32 s78, 0x7400
	s_cmp_le_u32 s30, s1
	v_add3_u32 v206, s26, v177, v178
	ds_read_b128 v[98:101], v206
	ds_read_b128 v[102:105], v206 offset:32
	ds_read_b128 v[106:109], v206 offset:64
	ds_read_b128 v[110:113], v206 offset:96
	ds_read_b128 v[190:193], v206 offset:4608
	ds_read_b128 v[214:217], v206 offset:4640
	ds_read_b128 v[244:247], v206 offset:4672
	ds_read_b128 v[206:209], v206 offset:4704
	s_setprio 1
	s_waitcnt lgkmcnt(7)
	v_mfma_f32_32x32x16_bf16 v[82:97], v[98:101], v[126:129], v[66:81]
	s_waitcnt lgkmcnt(6)
	v_mfma_f32_32x32x16_bf16 v[82:97], v[102:105], v[130:133], v[82:97]
	s_waitcnt lgkmcnt(5)
	v_mfma_f32_32x32x16_bf16 v[82:97], v[106:109], v[134:137], v[82:97]
	s_waitcnt lgkmcnt(4)
	v_mfma_f32_32x32x16_bf16 v[82:97], v[110:113], v[138:141], v[82:97]
	v_add3_u32 v166, s78, v174, v0
	v_add_u32_e32 v167, s78, v144
	v_add_u32_e32 v168, v167, v175
	v_add_u32_e32 v167, v167, v176
	s_waitcnt vmcnt(2)
	ds_write_b128 v166, v[114:117]
	s_waitcnt lgkmcnt(4)
	v_mfma_f32_32x32x16_bf16 v[98:113], v[190:193], v[126:129], v[66:81]
	s_waitcnt vmcnt(1)
	ds_write_b128 v168, v[118:121] offset:9216
	s_waitcnt lgkmcnt(4)
	v_mfma_f32_32x32x16_bf16 v[98:113], v[214:217], v[130:133], v[98:113]
	s_waitcnt vmcnt(0)
	ds_write_b128 v167, v[122:125] offset:9216
	s_waitcnt lgkmcnt(4)
	v_mfma_f32_32x32x16_bf16 v[98:113], v[244:247], v[134:137], v[98:113]
	s_waitcnt lgkmcnt(3)
	v_mfma_f32_32x32x16_bf16 v[98:113], v[206:209], v[138:141], v[98:113]
	s_setprio 0
	s_cbranch_scc1 .LBB0_69
	v_add_u32_e32 v190, s22, v179
	v_cmp_le_i32_e32 vcc, v190, v183
	v_add_u32_e32 v191, 2, v190
	s_nop 7
	v_cndmask_b32_e32 v98, v220, v98, vcc
	v_cmp_lt_i32_e32 vcc, v190, v173
	s_nop 1
	v_cndmask_b32_e32 v83, v220, v83, vcc
	v_cmp_le_i32_e32 vcc, v190, v173
	s_nop 1
	v_cndmask_b32_e32 v82, v220, v82, vcc
	v_cmp_le_i32_e32 vcc, v190, v184
	s_nop 1
	v_cndmask_b32_e32 v99, v220, v99, vcc
	v_cmp_le_i32_e32 vcc, v191, v173
	v_add_u32_e32 v191, 3, v190
	s_nop 0
	v_cndmask_b32_e32 v84, v220, v84, vcc
	v_cmp_le_i32_e32 vcc, v190, v185
	s_nop 1
	v_cndmask_b32_e32 v100, v220, v100, vcc
	v_cmp_le_i32_e32 vcc, v191, v173
	s_nop 1
	v_cndmask_b32_e32 v85, v220, v85, vcc
	v_cmp_le_i32_e32 vcc, v190, v186
	s_nop 1
	v_cndmask_b32_e32 v101, v220, v101, vcc
	v_cmp_le_i32_e32 vcc, v190, v187
	s_nop 1
	v_cndmask_b32_e32 v86, v220, v86, vcc
	v_cmp_le_i32_e32 vcc, v190, v188
	s_nop 1
	v_cndmask_b32_e32 v102, v220, v102, vcc
	v_cmp_le_i32_e32 vcc, v190, v189
	s_nop 1
	v_cndmask_b32_e32 v87, v220, v87, vcc
	v_cmp_le_i32_e32 vcc, v190, v195
	s_nop 1
	v_cndmask_b32_e32 v103, v220, v103, vcc
	v_cmp_le_i32_e32 vcc, v190, v196
	s_nop 1
	v_cndmask_b32_e32 v88, v220, v88, vcc
	v_cmp_le_i32_e32 vcc, v190, v197
	s_nop 1
	v_cndmask_b32_e32 v104, v220, v104, vcc
	v_cmp_le_i32_e32 vcc, v190, v198
	s_nop 1
	v_cndmask_b32_e32 v89, v220, v89, vcc
	v_cmp_le_i32_e32 vcc, v190, v199
	s_nop 1
	v_cndmask_b32_e32 v105, v220, v105, vcc
	v_cmp_le_i32_e32 vcc, v190, v200
	s_nop 1
	v_cndmask_b32_e32 v90, v220, v90, vcc
	v_cmp_le_i32_e32 vcc, v190, v201
	s_nop 1
	v_cndmask_b32_e32 v106, v220, v106, vcc
	v_cmp_le_i32_e32 vcc, v190, v202
	s_nop 1
	v_cndmask_b32_e32 v91, v220, v91, vcc
	v_cmp_le_i32_e32 vcc, v190, v203
	s_nop 1
	v_cndmask_b32_e32 v107, v220, v107, vcc
	v_cmp_le_i32_e32 vcc, v190, v204
	s_nop 1
	v_cndmask_b32_e32 v92, v220, v92, vcc
	v_cmp_le_i32_e32 vcc, v190, v205
	s_nop 1
	v_cndmask_b32_e32 v108, v220, v108, vcc
	v_cmp_le_i32_e32 vcc, v190, v228
	s_nop 1
	v_cndmask_b32_e32 v93, v220, v93, vcc
	v_cmp_le_i32_e32 vcc, v190, v229
	s_nop 1
	v_cndmask_b32_e32 v109, v220, v109, vcc
	v_cmp_le_i32_e32 vcc, v190, v230
	s_nop 1
	v_cndmask_b32_e32 v94, v220, v94, vcc
	v_cmp_le_i32_e32 vcc, v190, v231
	s_nop 1
	v_cndmask_b32_e32 v110, v220, v110, vcc
	v_cmp_le_i32_e32 vcc, v190, v232
	s_nop 1
	v_cndmask_b32_e32 v95, v220, v95, vcc
	v_cmp_le_i32_e32 vcc, v190, v233
	s_nop 1
	v_cndmask_b32_e32 v111, v220, v111, vcc
	v_cmp_le_i32_e32 vcc, v190, v234
	s_nop 1
	v_cndmask_b32_e32 v96, v220, v96, vcc
	v_cmp_le_i32_e32 vcc, v190, v235
	s_nop 1
	v_cndmask_b32_e32 v112, v220, v112, vcc
	v_cmp_le_i32_e32 vcc, v190, v236
	s_nop 1
	v_cndmask_b32_e32 v97, v220, v97, vcc
	v_cmp_le_i32_e32 vcc, v190, v237
	s_nop 1
	v_cndmask_b32_e32 v113, v220, v113, vcc

.LBB0_81:
	s_add_i32 s23, s22, -1
	s_and_b32 s23, s23, 1
	s_cmp_gt_u32 s4, s11
	s_cbranch_scc1 .LBB0_88
	s_mul_i32 s26, s23, 0x7400
	s_add_i32 s26, s26, 0
	s_add_i32 s30, s4, 63
	s_xor_b32 s78, s23, 1
	s_mulk_i32 s78, 0x7400
	s_cmp_le_u32 s30, s1
	v_add3_u32 v152, s26, v177, v178
	ds_read_b128 v[98:101], v152
	ds_read_b128 v[102:105], v152 offset:32
	ds_read_b128 v[106:109], v152 offset:64
	ds_read_b128 v[110:113], v152 offset:96
	ds_read_b128 v[154:157], v152 offset:4608
	ds_read_b128 v[162:165], v152 offset:4640
	ds_read_b128 v[190:193], v152 offset:4672
	ds_read_b128 v[206:209], v152 offset:4704
	s_setprio 1
	s_waitcnt lgkmcnt(7)
	v_mfma_f32_32x32x16_bf16 v[82:97], v[98:101], v[118:121], v[66:81]
	s_waitcnt lgkmcnt(6)
	v_mfma_f32_32x32x16_bf16 v[82:97], v[102:105], v[122:125], v[82:97]
	s_waitcnt lgkmcnt(5)
	v_mfma_f32_32x32x16_bf16 v[82:97], v[106:109], v[126:129], v[82:97]
	s_waitcnt lgkmcnt(4)
	v_mfma_f32_32x32x16_bf16 v[82:97], v[110:113], v[134:137], v[82:97]
	v_add3_u32 v166, s78, v174, v0
	v_add_u32_e32 v167, s78, v144
	v_add_u32_e32 v168, v167, v175
	v_add_u32_e32 v167, v167, v176
	s_waitcnt vmcnt(2)
	ds_write_b128 v166, v[114:117]
	s_waitcnt lgkmcnt(4)
	v_mfma_f32_32x32x16_bf16 v[98:113], v[154:157], v[118:121], v[66:81]
	s_waitcnt vmcnt(1)
	ds_write_b128 v168, v[130:133] offset:9216
	s_waitcnt lgkmcnt(4)
	v_mfma_f32_32x32x16_bf16 v[98:113], v[162:165], v[122:125], v[98:113]
	s_waitcnt vmcnt(0)
	ds_write_b128 v167, v[138:141] offset:9216
	s_waitcnt lgkmcnt(4)
	v_mfma_f32_32x32x16_bf16 v[98:113], v[190:193], v[126:129], v[98:113]
	s_waitcnt lgkmcnt(3)
	v_mfma_f32_32x32x16_bf16 v[98:113], v[206:209], v[134:137], v[98:113]
	s_setprio 0
	s_cbranch_scc1 .LBB0_84
	v_add_u32_e32 v152, s4, v179
	v_cmp_le_i32_e32 vcc, v152, v183
	v_add_u32_e32 v154, 2, v152
	s_nop 7
	v_cndmask_b32_e32 v98, v220, v98, vcc
	v_cmp_lt_i32_e32 vcc, v152, v173
	s_nop 1
	v_cndmask_b32_e32 v83, v220, v83, vcc
	v_cmp_le_i32_e32 vcc, v152, v173
	s_nop 1
	v_cndmask_b32_e32 v82, v220, v82, vcc
	v_cmp_le_i32_e32 vcc, v152, v184
	s_nop 1
	v_cndmask_b32_e32 v99, v220, v99, vcc
	v_cmp_le_i32_e32 vcc, v154, v173
	v_add_u32_e32 v154, 3, v152
	s_nop 0
	v_cndmask_b32_e32 v84, v220, v84, vcc
	v_cmp_le_i32_e32 vcc, v152, v185
	s_nop 1
	v_cndmask_b32_e32 v100, v220, v100, vcc
	v_cmp_le_i32_e32 vcc, v154, v173
	s_nop 1
	v_cndmask_b32_e32 v85, v220, v85, vcc
	v_cmp_le_i32_e32 vcc, v152, v186
	s_nop 1
	v_cndmask_b32_e32 v101, v220, v101, vcc
	v_cmp_le_i32_e32 vcc, v152, v187
	s_nop 1
	v_cndmask_b32_e32 v86, v220, v86, vcc
	v_cmp_le_i32_e32 vcc, v152, v188
	s_nop 1
	v_cndmask_b32_e32 v102, v220, v102, vcc
	v_cmp_le_i32_e32 vcc, v152, v189
	s_nop 1
	v_cndmask_b32_e32 v87, v220, v87, vcc
	v_cmp_le_i32_e32 vcc, v152, v195
	s_nop 1
	v_cndmask_b32_e32 v103, v220, v103, vcc
	v_cmp_le_i32_e32 vcc, v152, v196
	s_nop 1
	v_cndmask_b32_e32 v88, v220, v88, vcc
	v_cmp_le_i32_e32 vcc, v152, v197
	s_nop 1
	v_cndmask_b32_e32 v104, v220, v104, vcc
	v_cmp_le_i32_e32 vcc, v152, v198
	s_nop 1
	v_cndmask_b32_e32 v89, v220, v89, vcc
	v_cmp_le_i32_e32 vcc, v152, v199
	s_nop 1
	v_cndmask_b32_e32 v105, v220, v105, vcc
	v_cmp_le_i32_e32 vcc, v152, v200
	s_nop 1
	v_cndmask_b32_e32 v90, v220, v90, vcc
	v_cmp_le_i32_e32 vcc, v152, v201
	s_nop 1
	v_cndmask_b32_e32 v106, v220, v106, vcc
	v_cmp_le_i32_e32 vcc, v152, v202
	s_nop 1
	v_cndmask_b32_e32 v91, v220, v91, vcc
	v_cmp_le_i32_e32 vcc, v152, v203
	s_nop 1
	v_cndmask_b32_e32 v107, v220, v107, vcc
	v_cmp_le_i32_e32 vcc, v152, v204
	s_nop 1
	v_cndmask_b32_e32 v92, v220, v92, vcc
	v_cmp_le_i32_e32 vcc, v152, v205
	s_nop 1
	v_cndmask_b32_e32 v108, v220, v108, vcc
	v_cmp_le_i32_e32 vcc, v152, v228
	s_nop 1
	v_cndmask_b32_e32 v93, v220, v93, vcc
	v_cmp_le_i32_e32 vcc, v152, v229
	s_nop 1
	v_cndmask_b32_e32 v109, v220, v109, vcc
	v_cmp_le_i32_e32 vcc, v152, v230
	s_nop 1
	v_cndmask_b32_e32 v94, v220, v94, vcc
	v_cmp_le_i32_e32 vcc, v152, v231
	s_nop 1
	v_cndmask_b32_e32 v110, v220, v110, vcc
	v_cmp_le_i32_e32 vcc, v152, v232
	s_nop 1
	v_cndmask_b32_e32 v95, v220, v95, vcc
	v_cmp_le_i32_e32 vcc, v152, v233
	s_nop 1
	v_cndmask_b32_e32 v111, v220, v111, vcc
	v_cmp_le_i32_e32 vcc, v152, v234
	s_nop 1
	v_cndmask_b32_e32 v96, v220, v96, vcc
	v_cmp_le_i32_e32 vcc, v152, v235
	s_nop 1
	v_cndmask_b32_e32 v112, v220, v112, vcc
	v_cmp_le_i32_e32 vcc, v152, v236
	s_nop 1
	v_cndmask_b32_e32 v97, v220, v97, vcc
	v_cmp_le_i32_e32 vcc, v152, v237
	s_nop 1
	v_cndmask_b32_e32 v113, v220, v113, vcc
